# in-proj GEMM: hand-written main loop (line-sharing K-tile pairs, register staging) + LDS-transposed epilogue for all tiles except the dt column tile
# speedup vs baseline: 1.0006x; 1.0006x over previous
; DI int TID() { int t = threadIdx.x; asm volatile("" : "+v"(t)); return t; }
; template <bool SWAP, int MI, class AF, class BF, class EF>
; DI void gemm_tile(const AF& af, const BF& bfn, const EF& ef, int m0, int n0, int K, char* smem) {
;   constexpr int AROWS = MI * 64;
;   u16* As = (u16*)smem;
;   u16* Bs = As + 2 * AROWS * 40;
;   const int tid = TID(), lane = tid & 63, w = tid >> 6;
;   const int wm = w >> 1, wn = w & 1, l32 = lane & 31, h = lane >> 5;
;   const int lrow = (tid >> 6) * 16 + ((tid >> 5) & 1) * 8 + ((tid >> 2) & 1) * 4 + ((tid >> 3) & 3), lk = (tid & 3) * 8;
;   f32x16 acc[MI][2];
; #pragma unroll
;   for (int i = 0; i < MI; ++i)
; #pragma unroll
;     for (int j = 0; j < 2; ++j)
; #pragma unroll
;       for (int r = 0; r < 16; ++r) acc[i][j][r] = 0.f;
;   u32x4 ra[MI], rb[2];
;   const int nk = K >> 5;
; #pragma unroll
;   for (int i = 0; i < MI; ++i) ra[i] = *(const u32x4*)af(m0 + lrow + 64 * i, lk);
; #pragma unroll
;   for (int i = 0; i < 2; ++i) rb[i] = *(const u32x4*)bfn(n0 + lrow + 64 * i, lk);
; #pragma unroll
;   for (int i = 0; i < MI; ++i) *(u32x4*)&As[(lrow + 64 * i) * 40 + lk] = ra[i];
; #pragma unroll
;   for (int i = 0; i < 2; ++i) *(u32x4*)&Bs[(lrow + 64 * i) * 40 + lk] = rb[i];
;   {
;     const int k1 = (nk > 1) ? 32 + lk : lk;
; #pragma unroll
;     for (int i = 0; i < MI; ++i) ra[i] = *(const u32x4*)af(m0 + lrow + 64 * i, k1);
; #pragma unroll
;     for (int i = 0; i < 2; ++i) rb[i] = *(const u32x4*)bfn(n0 + lrow + 64 * i, k1);
;   }
;   __syncthreads();
; DI void phase_inproj(const Params& p, int l, int bid, int nblk, char* smem) {
;     ...
;     if (nt >= 18 && nt < 22) gemm_tile<false, 4>(af, bfn, efN, mt * 256, nt * 128, 1024, smem);
;     else gemm_tile<true, 4>(af, bfn, efT, mt * 256, nt * 128, 1024, smem);
.LBB0_423:
	s_sub_i32 s0, s35, 18
	s_lshl_b32 s73, s34, 8
	s_lshl_b32 s72, s35, 7
	s_cmp_gt_u32 s0, 3
	s_mov_b64 s[0:1], -1
	s_cbranch_scc0 .LBB0_747
	s_cmpk_eq_u32 s72, 0xb00
	s_cbranch_scc1 .Lip_orig
	v_lshrrev_b32_e32 v128, 6, v218
	v_bfe_u32 v129, v218, 5, 1
	v_bfe_u32 v130, v218, 2, 1
	v_bfe_u32 v131, v218, 3, 2
	v_lshlrev_b32_e32 v132, 4, v128
	v_lshl_add_u32 v132, v129, 3, v132
	v_lshl_add_u32 v132, v130, 2, v132
	v_add_u32_e32 v132, v132, v131
	v_and_b32_e32 v133, 3, v218
	v_lshlrev_b32_e32 v133, 4, v133
	v_lshl_add_u32 v200, v132, 11, v133
	v_mul_u32_u24_e32 v134, 80, v132
	v_add_u32_e32 v202, v134, v133
	v_and_b32_e32 v135, 31, v218
	v_lshrrev_b32_e32 v136, 7, v218
	v_bfe_u32 v137, v218, 6, 1
	v_lshl_add_u32 v136, v136, 7, v135
	v_lshl_add_u32 v137, v137, 6, v135
	v_mul_u32_u24_e32 v136, 80, v136
	v_mul_u32_u24_e32 v137, 80, v137
	v_lshl_add_u32 v206, v129, 4, v136
	v_lshl_add_u32 v207, v129, 4, v137
	s_add_i32 s56, s73, 0
	s_lshl_b32 s56, s56, 11
	s_add_u32 s26, s6, s56
	s_addc_u32 s27, s7, 0
	s_add_i32 s56, s73, 64
	s_lshl_b32 s56, s56, 11
	s_add_u32 s28, s6, s56
	s_addc_u32 s29, s7, 0
	s_add_i32 s56, s73, 128
	s_lshl_b32 s56, s56, 11
	s_add_u32 s30, s6, s56
	s_addc_u32 s31, s7, 0
	s_add_i32 s56, s73, 192
	s_lshl_b32 s56, s56, 11
	s_add_u32 s36, s6, s56
	s_addc_u32 s37, s7, 0
	s_add_i32 s56, s72, 0
	s_lshl_b32 s56, s56, 11
	s_add_u32 s42, s50, s56
	s_addc_u32 s43, s51, 0
	s_add_i32 s56, s72, 64
	s_lshl_b32 s56, s56, 11
	s_add_u32 s48, s50, s56
	s_addc_u32 s49, s51, 0
	v_mov_b64_e32 v[0:1], 0
	v_mov_b64_e32 v[2:3], 0
	v_mov_b64_e32 v[4:5], 0
	v_mov_b64_e32 v[6:7], 0
	v_mov_b64_e32 v[8:9], 0
	v_mov_b64_e32 v[10:11], 0
	v_mov_b64_e32 v[12:13], 0
	v_mov_b64_e32 v[14:15], 0
	v_mov_b64_e32 v[16:17], 0
	v_mov_b64_e32 v[18:19], 0
	v_mov_b64_e32 v[20:21], 0
	v_mov_b64_e32 v[22:23], 0
	v_mov_b64_e32 v[24:25], 0
	v_mov_b64_e32 v[26:27], 0
	v_mov_b64_e32 v[28:29], 0
	v_mov_b64_e32 v[30:31], 0
	v_mov_b64_e32 v[32:33], 0
	v_mov_b64_e32 v[34:35], 0
	v_mov_b64_e32 v[36:37], 0
	v_mov_b64_e32 v[38:39], 0
	v_mov_b64_e32 v[40:41], 0
	v_mov_b64_e32 v[42:43], 0
	v_mov_b64_e32 v[44:45], 0
	v_mov_b64_e32 v[46:47], 0
	v_mov_b64_e32 v[48:49], 0
	v_mov_b64_e32 v[50:51], 0
	v_mov_b64_e32 v[52:53], 0
	v_mov_b64_e32 v[54:55], 0
	v_mov_b64_e32 v[56:57], 0
	v_mov_b64_e32 v[58:59], 0
	v_mov_b64_e32 v[60:61], 0
	v_mov_b64_e32 v[62:63], 0
	v_mov_b64_e32 v[64:65], 0
	v_mov_b64_e32 v[66:67], 0
	v_mov_b64_e32 v[68:69], 0
	v_mov_b64_e32 v[70:71], 0
	v_mov_b64_e32 v[72:73], 0
	v_mov_b64_e32 v[74:75], 0
	v_mov_b64_e32 v[76:77], 0
	v_mov_b64_e32 v[78:79], 0
	v_mov_b64_e32 v[80:81], 0
	v_mov_b64_e32 v[82:83], 0
	v_mov_b64_e32 v[84:85], 0
	v_mov_b64_e32 v[86:87], 0
	v_mov_b64_e32 v[88:89], 0
	v_mov_b64_e32 v[90:91], 0
	v_mov_b64_e32 v[92:93], 0
	v_mov_b64_e32 v[94:95], 0
	v_mov_b64_e32 v[96:97], 0
	v_mov_b64_e32 v[98:99], 0
	v_mov_b64_e32 v[100:101], 0
	v_mov_b64_e32 v[102:103], 0
	v_mov_b64_e32 v[104:105], 0
	v_mov_b64_e32 v[106:107], 0
	v_mov_b64_e32 v[108:109], 0
	v_mov_b64_e32 v[110:111], 0
	v_mov_b64_e32 v[112:113], 0
	v_mov_b64_e32 v[114:115], 0
	v_mov_b64_e32 v[116:117], 0
	v_mov_b64_e32 v[118:119], 0
	v_mov_b64_e32 v[120:121], 0
	v_mov_b64_e32 v[122:123], 0
	v_mov_b64_e32 v[124:125], 0
	v_mov_b64_e32 v[126:127], 0
	s_mov_b32 s64, 0
	v_add_u32_e32 v201, s64, v200
	global_load_dwordx4 v[128:131], v201, s[26:27]
	global_load_dwordx4 v[152:155], v201, s[26:27] offset:64
	global_load_dwordx4 v[132:135], v201, s[28:29]
	global_load_dwordx4 v[156:159], v201, s[28:29] offset:64
	global_load_dwordx4 v[136:139], v201, s[30:31]
	global_load_dwordx4 v[160:163], v201, s[30:31] offset:64
	global_load_dwordx4 v[140:143], v201, s[36:37]
	global_load_dwordx4 v[164:167], v201, s[36:37] offset:64
	global_load_dwordx4 v[144:147], v201, s[42:43]
	global_load_dwordx4 v[168:171], v201, s[42:43] offset:64
	global_load_dwordx4 v[148:151], v201, s[48:49]
	global_load_dwordx4 v[176:179], v201, s[48:49] offset:64
	s_add_i32 s64, s64, 0x80
	s_movk_i32 s65, 16
	s_waitcnt vmcnt(0)
	ds_write_b128 v202, v[128:131] offset:0
	ds_write_b128 v202, v[132:135] offset:5120
	ds_write_b128 v202, v[136:139] offset:10240
	ds_write_b128 v202, v[140:143] offset:15360
	ds_write_b128 v202, v[144:147] offset:40960
	ds_write_b128 v202, v[148:151] offset:46080
	s_waitcnt lgkmcnt(0)
	s_barrier
	ds_read_b128 v[196:199], v207 offset:40960
	ds_read_b128 v[228:231], v207 offset:43520
	ds_read_b128 v[180:183], v206 offset:0
	ds_read_b128 v[184:187], v206 offset:2560
	ds_read_b128 v[188:191], v206 offset:5120
	ds_read_b128 v[192:195], v206 offset:7680
; template <bool SWAP, int MI, class AF, class BF, class EF>
; DI void gemm_tile(const AF& af, const BF& bfn, const EF& ef, int m0, int n0, int K, char* smem) {
;     ...
;   for (int kt = 0; kt < nk; ++kt) {
;     const int cur = kt & 1;
;     const u16* Ab = As + cur * AROWS * 40;
;     const u16* Bb = Bs + cur * 128 * 40;
; #pragma unroll
;     for (int ks = 0; ks < 2; ++ks) {
;       bf16x8 a[MI], b[2];
; #pragma unroll
;       for (int i = 0; i < MI; ++i) a[i] = *(const bf16x8*)&Ab[(wm * (MI * 32) + i * 32 + l32) * 40 + ks * 16 + h * 8];
; #pragma unroll
;       for (int i = 0; i < 2; ++i) b[i] = *(const bf16x8*)&Bb[(wn * 64 + i * 32 + l32) * 40 + ks * 16 + h * 8];
; #pragma unroll
;       for (int i = 0; i < MI; ++i)
; #pragma unroll
;         for (int j = 0; j < 2; ++j)
;           acc[i][j] = SWAP ? __builtin_amdgcn_mfma_f32_32x32x16_bf16(b[j], a[i], acc[i][j], 0, 0, 0)
;                            : __builtin_amdgcn_mfma_f32_32x32x16_bf16(a[i], b[j], acc[i][j], 0, 0, 0);
;     }
;     {
;       u16* An = As + (cur ^ 1) * AROWS * 40;
;       u16* Bn = Bs + (cur ^ 1) * 128 * 40;
; #pragma unroll
;       for (int i = 0; i < MI; ++i) *(u32x4*)&An[(lrow + 64 * i) * 40 + lk] = ra[i];
; #pragma unroll
;       for (int i = 0; i < 2; ++i) *(u32x4*)&Bn[(lrow + 64 * i) * 40 + lk] = rb[i];
;       const int kn = (kt + 2 < nk) ? kt + 2 : nk - 1;
;       const int k0 = kn * 32 + lk;
; #pragma unroll
;       for (int i = 0; i < MI; ++i) ra[i] = *(const u32x4*)af(m0 + lrow + 64 * i, k0);
; #pragma unroll
;       for (int i = 0; i < 2; ++i) rb[i] = *(const u32x4*)bfn(n0 + lrow + 64 * i, k0);
;     }
;     __syncthreads();
;   }
.Lgemm_ipt_loop:
	ds_read_b128 v[232:235], v207 offset:40992
	ds_read_b128 v[236:239], v207 offset:43552
	ds_read_b128 v[220:223], v206 offset:32
	ds_read_b128 v[240:243], v206 offset:2592
	ds_read_b128 v[244:247], v206 offset:5152
	ds_read_b128 v[248:251], v206 offset:7712
	s_waitcnt lgkmcnt(9)
	v_mfma_f32_32x32x16_bf16 v[112:127], v[196:199], v[180:183], v[112:127]
	v_mfma_f32_32x32x16_bf16 v[96:111], v[228:231], v[180:183], v[96:111]
	s_waitcnt lgkmcnt(8)
	v_mfma_f32_32x32x16_bf16 v[80:95], v[196:199], v[184:187], v[80:95]
	v_mfma_f32_32x32x16_bf16 v[64:79], v[228:231], v[184:187], v[64:79]
	ds_write_b128 v202, v[152:155] offset:20480
	ds_write_b128 v202, v[156:159] offset:25600
	ds_write_b128 v202, v[160:163] offset:30720
	ds_write_b128 v202, v[164:167] offset:35840
	ds_write_b128 v202, v[168:171] offset:51200
	ds_write_b128 v202, v[176:179] offset:56320
	v_add_u32_e32 v201, s64, v200
	global_load_dwordx4 v[128:131], v201, s[26:27]
	global_load_dwordx4 v[152:155], v201, s[26:27] offset:64
	global_load_dwordx4 v[132:135], v201, s[28:29]
	global_load_dwordx4 v[156:159], v201, s[28:29] offset:64
	global_load_dwordx4 v[136:139], v201, s[30:31]
	global_load_dwordx4 v[160:163], v201, s[30:31] offset:64
	global_load_dwordx4 v[140:143], v201, s[36:37]
	global_load_dwordx4 v[164:167], v201, s[36:37] offset:64
	global_load_dwordx4 v[144:147], v201, s[42:43]
	global_load_dwordx4 v[168:171], v201, s[42:43] offset:64
	global_load_dwordx4 v[148:151], v201, s[48:49]
	global_load_dwordx4 v[176:179], v201, s[48:49] offset:64
	s_add_i32 s64, s64, 0x80
	s_min_u32 s64, s64, 0x780
	s_waitcnt lgkmcnt(13)
	v_mfma_f32_32x32x16_bf16 v[48:63], v[196:199], v[188:191], v[48:63]
	v_mfma_f32_32x32x16_bf16 v[32:47], v[228:231], v[188:191], v[32:47]
	s_waitcnt lgkmcnt(12)
	v_mfma_f32_32x32x16_bf16 v[16:31], v[196:199], v[192:195], v[16:31]
	v_mfma_f32_32x32x16_bf16 v[0:15], v[228:231], v[192:195], v[0:15]
	s_waitcnt lgkmcnt(0)
	s_barrier
	ds_read_b128 v[196:199], v207 offset:51200
	ds_read_b128 v[228:231], v207 offset:53760
	ds_read_b128 v[180:183], v206 offset:20480
	ds_read_b128 v[184:187], v206 offset:23040
	ds_read_b128 v[188:191], v206 offset:25600
	ds_read_b128 v[192:195], v206 offset:28160
	v_mfma_f32_32x32x16_bf16 v[112:127], v[232:235], v[220:223], v[112:127]
	v_mfma_f32_32x32x16_bf16 v[96:111], v[236:239], v[220:223], v[96:111]
	v_mfma_f32_32x32x16_bf16 v[80:95], v[232:235], v[240:243], v[80:95]
	v_mfma_f32_32x32x16_bf16 v[64:79], v[236:239], v[240:243], v[64:79]
	v_mfma_f32_32x32x16_bf16 v[48:63], v[232:235], v[244:247], v[48:63]
	v_mfma_f32_32x32x16_bf16 v[32:47], v[236:239], v[244:247], v[32:47]
	v_mfma_f32_32x32x16_bf16 v[16:31], v[232:235], v[248:251], v[16:31]
	v_mfma_f32_32x32x16_bf16 v[0:15], v[236:239], v[248:251], v[0:15]
	ds_read_b128 v[232:235], v207 offset:51232
	ds_read_b128 v[236:239], v207 offset:53792
	ds_read_b128 v[220:223], v206 offset:20512
	ds_read_b128 v[240:243], v206 offset:23072
	ds_read_b128 v[244:247], v206 offset:25632
	ds_read_b128 v[248:251], v206 offset:28192
	s_waitcnt lgkmcnt(9)
	v_mfma_f32_32x32x16_bf16 v[112:127], v[196:199], v[180:183], v[112:127]
	v_mfma_f32_32x32x16_bf16 v[96:111], v[228:231], v[180:183], v[96:111]
	s_waitcnt lgkmcnt(8)
	v_mfma_f32_32x32x16_bf16 v[80:95], v[196:199], v[184:187], v[80:95]
	v_mfma_f32_32x32x16_bf16 v[64:79], v[228:231], v[184:187], v[64:79]
	s_waitcnt vmcnt(0)
	ds_write_b128 v202, v[128:131] offset:0
	ds_write_b128 v202, v[132:135] offset:5120
	ds_write_b128 v202, v[136:139] offset:10240
	ds_write_b128 v202, v[140:143] offset:15360
	ds_write_b128 v202, v[144:147] offset:40960
	ds_write_b128 v202, v[148:151] offset:46080
	s_waitcnt lgkmcnt(13)
	v_mfma_f32_32x32x16_bf16 v[48:63], v[196:199], v[188:191], v[48:63]
	v_mfma_f32_32x32x16_bf16 v[32:47], v[228:231], v[188:191], v[32:47]
	s_waitcnt lgkmcnt(12)
	v_mfma_f32_32x32x16_bf16 v[16:31], v[196:199], v[192:195], v[16:31]
	v_mfma_f32_32x32x16_bf16 v[0:15], v[228:231], v[192:195], v[0:15]
	s_waitcnt lgkmcnt(0)
	s_barrier
	ds_read_b128 v[196:199], v207 offset:40960
	ds_read_b128 v[228:231], v207 offset:43520
	ds_read_b128 v[180:183], v206 offset:0
	ds_read_b128 v[184:187], v206 offset:2560
	ds_read_b128 v[188:191], v206 offset:5120
	ds_read_b128 v[192:195], v206 offset:7680
	v_mfma_f32_32x32x16_bf16 v[112:127], v[232:235], v[220:223], v[112:127]
	v_mfma_f32_32x32x16_bf16 v[96:111], v[236:239], v[220:223], v[96:111]
	v_mfma_f32_32x32x16_bf16 v[80:95], v[232:235], v[240:243], v[80:95]
	v_mfma_f32_32x32x16_bf16 v[64:79], v[236:239], v[240:243], v[64:79]
	v_mfma_f32_32x32x16_bf16 v[48:63], v[232:235], v[244:247], v[48:63]
	v_mfma_f32_32x32x16_bf16 v[32:47], v[236:239], v[244:247], v[32:47]
	v_mfma_f32_32x32x16_bf16 v[16:31], v[232:235], v[248:251], v[16:31]
	v_mfma_f32_32x32x16_bf16 v[0:15], v[236:239], v[248:251], v[0:15]
	s_add_i32 s65, s65, -1
	s_cmp_lg_u32 s65, 0
	s_cbranch_scc1 .Lgemm_ipt_loop
; DI u32 pack2(float a, float b) { return (u32)f2bf(a) | ((u32)f2bf(b) << 16); }
; template <bool SWAP, int MI, class AF, class BF, class EF>
; DI void gemm_tile(const AF& af, const BF& bfn, const EF& ef, int m0, int n0, int K, char* smem) {
;     ...
; #pragma unroll
;   for (int i = 0; i < MI; ++i)
; #pragma unroll
;     for (int j = 0; j < 2; ++j)
; #pragma unroll
;       for (int rg = 0; rg < 4; ++rg) {
;         const int m = SWAP ? (m0 + wm * (MI * 32) + i * 32 + l32) : (m0 + wm * (MI * 32) + i * 32 + rg * 8 + h * 4);
;         const int n = SWAP ? (n0 + wn * 64 + j * 32 + rg * 8 + h * 4) : (n0 + wn * 64 + j * 32 + l32);
;         ef(m, n, acc[i][j][rg * 4 + 0], acc[i][j][rg * 4 + 1], acc[i][j][rg * 4 + 2], acc[i][j][rg * 4 + 3]);
;       }
; DI void phase_inproj(const Params& p, int l, int bid, int nblk, char* smem) {
;     ...
;   auto efT = [=](int m, int n, float v0, float v1, float v2, float v3) {
;     const uint2 o = {pack2(v0, v1), pack2(v2, v3)};
;     if (n < 768) *(uint2*)&PHY[(size_t)m * 768 + n] = o;
;     else if (n < 1280) *(uint2*)&PZ[(size_t)m * 512 + (n - 768)] = o;
;     else if (n < 2304) *(uint2*)&PXBC[(size_t)m * 1024 + (n - 1280)] = o;
;     else if (n >= 2816 && n < 2832) { float4 f = {v0, v1, v2, v3}; *(float4*)&DT[(size_t)m * 16 + (n - 2816)] = f; }
;   };
	s_waitcnt lgkmcnt(0)
	s_waitcnt vmcnt(0)
	v_and_b32_e32 v128, 31, v218
	v_lshrrev_b32_e32 v129, 7, v218
	v_bfe_u32 v130, v218, 5, 1
	v_bfe_u32 v131, v218, 6, 1
	v_lshl_add_u32 v128, v129, 7, v128
	v_mul_u32_u24_e32 v128, 272, v128
	v_lshlrev_b32_e32 v131, 7, v131
	v_lshl_add_u32 v131, v130, 3, v131
	v_add_u32_e32 v128, v128, v131
	s_nop 7
	v_cvt_pk_bf16_f32 v112, v112, v113
	v_cvt_pk_bf16_f32 v113, v114, v115
	v_cvt_pk_bf16_f32 v116, v116, v117
	v_cvt_pk_bf16_f32 v117, v118, v119
	v_cvt_pk_bf16_f32 v120, v120, v121
	v_cvt_pk_bf16_f32 v121, v122, v123
	v_cvt_pk_bf16_f32 v124, v124, v125
	v_cvt_pk_bf16_f32 v125, v126, v127
	ds_write_b64 v128, v[112:113] offset:0
	ds_write_b64 v128, v[116:117] offset:16
	ds_write_b64 v128, v[120:121] offset:32
	ds_write_b64 v128, v[124:125] offset:48
	v_cvt_pk_bf16_f32 v96, v96, v97
	v_cvt_pk_bf16_f32 v97, v98, v99
	v_cvt_pk_bf16_f32 v100, v100, v101
	v_cvt_pk_bf16_f32 v101, v102, v103
	v_cvt_pk_bf16_f32 v104, v104, v105
	v_cvt_pk_bf16_f32 v105, v106, v107
	v_cvt_pk_bf16_f32 v108, v108, v109
	v_cvt_pk_bf16_f32 v109, v110, v111
	ds_write_b64 v128, v[96:97] offset:64
	ds_write_b64 v128, v[100:101] offset:80
	ds_write_b64 v128, v[104:105] offset:96
	ds_write_b64 v128, v[108:109] offset:112
	v_cvt_pk_bf16_f32 v80, v80, v81
	v_cvt_pk_bf16_f32 v81, v82, v83
	v_cvt_pk_bf16_f32 v84, v84, v85
	v_cvt_pk_bf16_f32 v85, v86, v87
	v_cvt_pk_bf16_f32 v88, v88, v89
	v_cvt_pk_bf16_f32 v89, v90, v91
	v_cvt_pk_bf16_f32 v92, v92, v93
	v_cvt_pk_bf16_f32 v93, v94, v95
	ds_write_b64 v128, v[80:81] offset:8704
	ds_write_b64 v128, v[84:85] offset:8720
	ds_write_b64 v128, v[88:89] offset:8736
	ds_write_b64 v128, v[92:93] offset:8752
	v_cvt_pk_bf16_f32 v64, v64, v65
	v_cvt_pk_bf16_f32 v65, v66, v67
	v_cvt_pk_bf16_f32 v68, v68, v69
	v_cvt_pk_bf16_f32 v69, v70, v71
	v_cvt_pk_bf16_f32 v72, v72, v73
	v_cvt_pk_bf16_f32 v73, v74, v75
	v_cvt_pk_bf16_f32 v76, v76, v77
	v_cvt_pk_bf16_f32 v77, v78, v79
	ds_write_b64 v128, v[64:65] offset:8768
	ds_write_b64 v128, v[68:69] offset:8784
	ds_write_b64 v128, v[72:73] offset:8800
	ds_write_b64 v128, v[76:77] offset:8816
	v_cvt_pk_bf16_f32 v48, v48, v49
	v_cvt_pk_bf16_f32 v49, v50, v51
	v_cvt_pk_bf16_f32 v52, v52, v53
	v_cvt_pk_bf16_f32 v53, v54, v55
	v_cvt_pk_bf16_f32 v56, v56, v57
	v_cvt_pk_bf16_f32 v57, v58, v59
	v_cvt_pk_bf16_f32 v60, v60, v61
	v_cvt_pk_bf16_f32 v61, v62, v63
	ds_write_b64 v128, v[48:49] offset:17408
	ds_write_b64 v128, v[52:53] offset:17424
	ds_write_b64 v128, v[56:57] offset:17440
	ds_write_b64 v128, v[60:61] offset:17456
	v_cvt_pk_bf16_f32 v32, v32, v33
	v_cvt_pk_bf16_f32 v33, v34, v35
	v_cvt_pk_bf16_f32 v36, v36, v37
	v_cvt_pk_bf16_f32 v37, v38, v39
	v_cvt_pk_bf16_f32 v40, v40, v41
	v_cvt_pk_bf16_f32 v41, v42, v43
	v_cvt_pk_bf16_f32 v44, v44, v45
	v_cvt_pk_bf16_f32 v45, v46, v47
	ds_write_b64 v128, v[32:33] offset:17472
	ds_write_b64 v128, v[36:37] offset:17488
	ds_write_b64 v128, v[40:41] offset:17504
	ds_write_b64 v128, v[44:45] offset:17520
	v_cvt_pk_bf16_f32 v16, v16, v17
	v_cvt_pk_bf16_f32 v17, v18, v19
	v_cvt_pk_bf16_f32 v20, v20, v21
	v_cvt_pk_bf16_f32 v21, v22, v23
	v_cvt_pk_bf16_f32 v24, v24, v25
	v_cvt_pk_bf16_f32 v25, v26, v27
	v_cvt_pk_bf16_f32 v28, v28, v29
	v_cvt_pk_bf16_f32 v29, v30, v31
	ds_write_b64 v128, v[16:17] offset:26112
	ds_write_b64 v128, v[20:21] offset:26128
	ds_write_b64 v128, v[24:25] offset:26144
	ds_write_b64 v128, v[28:29] offset:26160
	v_cvt_pk_bf16_f32 v0, v0, v1
	v_cvt_pk_bf16_f32 v1, v2, v3
	v_cvt_pk_bf16_f32 v4, v4, v5
	v_cvt_pk_bf16_f32 v5, v6, v7
	v_cvt_pk_bf16_f32 v8, v8, v9
	v_cvt_pk_bf16_f32 v9, v10, v11
	v_cvt_pk_bf16_f32 v12, v12, v13
	v_cvt_pk_bf16_f32 v13, v14, v15
	ds_write_b64 v128, v[0:1] offset:26176
	ds_write_b64 v128, v[4:5] offset:26192
	ds_write_b64 v128, v[8:9] offset:26208
	ds_write_b64 v128, v[12:13] offset:26224
	s_cmpk_lt_u32 s72, 0x300
	s_cbranch_scc1 .Left_phy
	s_cmpk_lt_u32 s72, 0x500
	s_cbranch_scc1 .Left_pz
	s_lshl_b32 s16, s73, 11
	s_lshl_b32 s17, s72, 1
	s_add_u32 s16, s16, s17
	s_add_u32 s16, s16, 0x59ff600
	s_movk_i32 s38, 0x800
	s_mov_b32 s39, 0x8000
	s_branch .Left_go

; DI int TID() { int t = threadIdx.x; asm volatile("" : "+v"(t)); return t; }
; template <bool SWAP, int MI, class AF, class BF, class EF>
; DI void gemm_tile(const AF& af, const BF& bfn, const EF& ef, int m0, int n0, int K, char* smem) {
;   constexpr int AROWS = MI * 64;
;   u16* As = (u16*)smem;
;   u16* Bs = As + 2 * AROWS * 40;
;   const int tid = TID(), lane = tid & 63, w = tid >> 6;
;   const int wm = w >> 1, wn = w & 1, l32 = lane & 31, h = lane >> 5;
;   const int lrow = (tid >> 6) * 16 + ((tid >> 5) & 1) * 8 + ((tid >> 2) & 1) * 4 + ((tid >> 3) & 3), lk = (tid & 3) * 8;
;   f32x16 acc[MI][2];
; #pragma unroll
;   for (int i = 0; i < MI; ++i)
; #pragma unroll
;     for (int j = 0; j < 2; ++j)
; #pragma unroll
;       for (int r = 0; r < 16; ++r) acc[i][j][r] = 0.f;
;   u32x4 ra[MI], rb[2];
;   const int nk = K >> 5;
; #pragma unroll
;   for (int i = 0; i < MI; ++i) ra[i] = *(const u32x4*)af(m0 + lrow + 64 * i, lk);
; #pragma unroll
;   for (int i = 0; i < 2; ++i) rb[i] = *(const u32x4*)bfn(n0 + lrow + 64 * i, lk);
; #pragma unroll
;   for (int i = 0; i < MI; ++i) *(u32x4*)&As[(lrow + 64 * i) * 40 + lk] = ra[i];
; #pragma unroll
;   for (int i = 0; i < 2; ++i) *(u32x4*)&Bs[(lrow + 64 * i) * 40 + lk] = rb[i];
;   {
;     const int k1 = (nk > 1) ? 32 + lk : lk;
; #pragma unroll
;     for (int i = 0; i < MI; ++i) ra[i] = *(const u32x4*)af(m0 + lrow + 64 * i, k1);
; #pragma unroll
;     for (int i = 0; i < 2; ++i) rb[i] = *(const u32x4*)bfn(n0 + lrow + 64 * i, k1);
;   }
;   __syncthreads();
.Lip_orig:
	v_mov_b32_e32 v175, v218
	s_mov_b64 s[0:1], 0x20000
	v_lshrrev_b32_e32 v0, 2, v175
	v_and_b32_e32 v1, 4, v175
	v_ashrrev_i32_e32 v4, 2, v175
	v_bfe_u32 v2, v175, 3, 2
	v_and_b32_e32 v4, -16, v4
	v_and_or_b32 v0, v0, 8, v1
	v_or3_b32 v15, v0, v4, v2
	v_lshlrev_b32_e32 v3, 3, v175
	v_add_u32_e32 v0, s73, v15
	v_and_b32_e32 v52, 24, v3
	v_ashrrev_i32_e32 v1, 31, v0
	v_lshlrev_b32_e32 v172, 1, v52
	v_lshlrev_b64 v[40:41], 11, v[0:1]
	v_lshl_add_u64 v[2:3], s[6:7], 0, v[172:173]
	v_lshl_add_u64 v[42:43], v[40:41], 0, s[0:1]
	v_lshl_add_u64 v[0:1], v[2:3], 0, v[40:41]
	v_lshl_add_u64 v[4:5], v[2:3], 0, v[42:43]
	global_load_dwordx4 v[16:19], v[0:1], off
	global_load_dwordx4 v[20:23], v[4:5], off
	v_add_u32_e32 v4, s72, v15
	s_mov_b64 s[16:17], 0x40000
	v_ashrrev_i32_e32 v5, 31, v4
	v_lshl_add_u64 v[44:45], v[40:41], 0, s[16:17]
	s_mov_b64 s[16:17], 0x60000
	v_lshlrev_b64 v[178:179], 11, v[4:5]
	v_lshl_add_u64 v[46:47], v[40:41], 0, s[16:17]
	v_lshl_add_u64 v[176:177], s[50:51], 0, v[172:173]
	v_lshl_add_u64 v[180:181], v[178:179], 0, s[0:1]
	v_lshl_add_u64 v[48:49], v[176:177], 0, v[178:179]
	v_lshl_add_u64 v[50:51], v[176:177], 0, v[180:181]
	v_or_b32_e32 v191, 64, v52
	v_add_u32_e32 v52, 0, v172
	v_or_b32_e32 v172, 64, v172
	v_lshl_add_u64 v[182:183], s[6:7], 0, v[40:41]
	v_lshl_add_u64 v[184:185], s[6:7], 0, v[42:43]
	v_lshl_add_u64 v[186:187], s[6:7], 0, v[44:45]
	v_lshl_add_u64 v[188:189], s[6:7], 0, v[46:47]
	v_lshl_add_u64 v[0:1], v[2:3], 0, v[44:45]
	v_lshl_add_u64 v[2:3], v[2:3], 0, v[46:47]
	global_load_dwordx4 v[24:27], v[48:49], off
	global_load_dwordx4 v[28:31], v[0:1], off
	global_load_dwordx4 v[32:35], v[2:3], off
	global_load_dwordx4 v[36:39], v[50:51], off
	global_load_dwordx4 v[144:147], v[48:49], off offset:64
	v_lshl_add_u64 v[40:41], v[182:183], 0, v[172:173]
	v_lshl_add_u64 v[42:43], v[184:185], 0, v[172:173]
	v_lshl_add_u64 v[44:45], v[186:187], 0, v[172:173]
	v_lshl_add_u64 v[46:47], v[188:189], 0, v[172:173]
	global_load_dwordx4 v[148:151], v[50:51], off offset:64
	global_load_dwordx4 v[128:131], v[40:41], off
	global_load_dwordx4 v[132:135], v[42:43], off
	global_load_dwordx4 v[136:139], v[44:45], off
	global_load_dwordx4 v[140:143], v[46:47], off
	v_bfe_u32 v190, v175, 5, 1
	v_and_b32_e32 v53, 0xfffff9f, v175
	v_and_b32_e32 v54, 0x5f, v175
	v_or_b32_e32 v55, 0x60, v175
	v_mul_lo_u32 v15, v15, s8
	v_mov_b32_e32 v0, 0
	v_lshl_add_u32 v56, v190, 4, 0
	v_mul_lo_u32 v53, v53, s8
	v_mul_lo_u32 v55, v55, s8
	v_mul_u32_u24_e32 v54, 0x50, v54
	v_add_u32_e32 v195, v52, v15
	s_mov_b32 s0, 0
	v_mov_b32_e32 v1, v0
	v_mov_b32_e32 v2, v0
	v_mov_b32_e32 v3, v0
	v_mov_b32_e32 v4, v0
	v_mov_b32_e32 v5, v0
	v_mov_b32_e32 v6, v0
	v_mov_b32_e32 v7, v0
	v_mov_b32_e32 v8, v0
	v_mov_b32_e32 v9, v0
	v_mov_b32_e32 v10, v0
	v_mov_b32_e32 v11, v0
	v_mov_b32_e32 v12, v0
	v_mov_b32_e32 v13, v0
	v_mov_b32_e32 v14, v0
	v_add_u32_e32 v192, v56, v53
	v_add_u32_e32 v193, v56, v55
	v_add_u32_e32 v194, v56, v54
	v_mov_b32_e32 v15, v0
	v_mov_b32_e32 v40, v0
	v_mov_b32_e32 v41, v0
	v_mov_b32_e32 v42, v0
	v_mov_b32_e32 v43, v0
	v_mov_b32_e32 v44, v0
	v_mov_b32_e32 v45, v0
	v_mov_b32_e32 v46, v0
	v_mov_b32_e32 v47, v0
	v_mov_b32_e32 v48, v0
	v_mov_b32_e32 v49, v0
	v_mov_b32_e32 v50, v0
	v_mov_b32_e32 v51, v0
	v_mov_b32_e32 v52, v0
	v_mov_b32_e32 v53, v0
	s_waitcnt vmcnt(11)
	ds_write_b128 v195, v[16:19]
	s_waitcnt vmcnt(9)
	ds_write_b128 v195, v[24:27] offset:40960
	ds_write_b128 v195, v[20:23] offset:5120
	s_waitcnt vmcnt(8)
	ds_write_b128 v195, v[28:31] offset:10240
	s_waitcnt vmcnt(7)
	ds_write_b128 v195, v[32:35] offset:15360
	s_waitcnt vmcnt(6)
	ds_write_b128 v195, v[36:39] offset:46080
	v_mov_b32_e32 v16, v0
	v_mov_b32_e32 v17, v0
	v_mov_b32_e32 v18, v0
	v_mov_b32_e32 v19, v0
	v_mov_b32_e32 v20, v0
	v_mov_b32_e32 v21, v0
	v_mov_b32_e32 v22, v0
	v_mov_b32_e32 v23, v0
	v_mov_b32_e32 v24, v0
	v_mov_b32_e32 v25, v0
	v_mov_b32_e32 v26, v0
	v_mov_b32_e32 v27, v0
	v_mov_b32_e32 v28, v0
	v_mov_b32_e32 v29, v0
	v_mov_b32_e32 v30, v0
	v_mov_b32_e32 v31, v0
	v_mov_b32_e32 v32, v0
	v_mov_b32_e32 v33, v0
	v_mov_b32_e32 v34, v0
	v_mov_b32_e32 v35, v0
	v_mov_b32_e32 v36, v0
	v_mov_b32_e32 v37, v0
	v_mov_b32_e32 v38, v0
	v_mov_b32_e32 v39, v0
	v_mov_b32_e32 v54, v0
	v_mov_b32_e32 v55, v0
	v_mov_b32_e32 v56, v0
	v_mov_b32_e32 v57, v0
	v_mov_b32_e32 v58, v0
	v_mov_b32_e32 v59, v0
	v_mov_b32_e32 v60, v0
	v_mov_b32_e32 v61, v0
	v_mov_b32_e32 v62, v0
	v_mov_b32_e32 v63, v0
	v_mov_b32_e32 v64, v0
	v_mov_b32_e32 v65, v0
	v_mov_b32_e32 v66, v0
	v_mov_b32_e32 v67, v0
	v_mov_b32_e32 v68, v0
	v_mov_b32_e32 v69, v0
	v_mov_b32_e32 v70, v0
	v_mov_b32_e32 v71, v0
	v_mov_b32_e32 v72, v0
	v_mov_b32_e32 v73, v0
	v_mov_b32_e32 v74, v0
	v_mov_b32_e32 v75, v0
	v_mov_b32_e32 v76, v0
	v_mov_b32_e32 v77, v0
	v_mov_b32_e32 v78, v0
	v_mov_b32_e32 v79, v0
	v_mov_b32_e32 v80, v0
	v_mov_b32_e32 v81, v0
	v_mov_b32_e32 v82, v0
	v_mov_b32_e32 v83, v0
	v_mov_b32_e32 v84, v0
	v_mov_b32_e32 v85, v0
	v_mov_b32_e32 v86, v0
	v_mov_b32_e32 v87, v0
	v_mov_b32_e32 v88, v0
	v_mov_b32_e32 v89, v0
	v_mov_b32_e32 v90, v0
	v_mov_b32_e32 v91, v0
	v_mov_b32_e32 v92, v0
	v_mov_b32_e32 v93, v0
	v_mov_b32_e32 v94, v0
	v_mov_b32_e32 v95, v0
	v_mov_b32_e32 v96, v0
	v_mov_b32_e32 v97, v0
	v_mov_b32_e32 v98, v0
	v_mov_b32_e32 v99, v0
	v_mov_b32_e32 v100, v0
	v_mov_b32_e32 v101, v0
	v_mov_b32_e32 v102, v0
	v_mov_b32_e32 v103, v0
	v_mov_b32_e32 v104, v0
	v_mov_b32_e32 v105, v0
	v_mov_b32_e32 v106, v0
	v_mov_b32_e32 v107, v0
	v_mov_b32_e32 v108, v0
	v_mov_b32_e32 v109, v0
	v_mov_b32_e32 v110, v0
	v_mov_b32_e32 v111, v0
	v_mov_b32_e32 v112, v0
	v_mov_b32_e32 v113, v0
	v_mov_b32_e32 v114, v0
	v_mov_b32_e32 v115, v0
	v_mov_b32_e32 v116, v0
	v_mov_b32_e32 v117, v0
	v_mov_b32_e32 v118, v0
	v_mov_b32_e32 v119, v0
	v_mov_b32_e32 v120, v0
	v_mov_b32_e32 v121, v0
	v_mov_b32_e32 v122, v0
	v_mov_b32_e32 v123, v0
	v_mov_b32_e32 v124, v0
	v_mov_b32_e32 v125, v0
	v_mov_b32_e32 v126, v0
	v_mov_b32_e32 v127, v0
	s_waitcnt lgkmcnt(0)
	s_barrier

; DI int TID() { int t = threadIdx.x; asm volatile("" : "+v"(t)); return t; }
; template <bool SWAP, int MI, class AF, class BF, class EF>
; DI void gemm_tile(const AF& af, const BF& bfn, const EF& ef, int m0, int n0, int K, char* smem) {
;   constexpr int AROWS = MI * 64;
;   u16* As = (u16*)smem;
;   u16* Bs = As + 2 * AROWS * 40;
;   const int tid = TID(), lane = tid & 63, w = tid >> 6;
;   const int wm = w >> 1, wn = w & 1, l32 = lane & 31, h = lane >> 5;
;   const int lrow = (tid >> 6) * 16 + ((tid >> 5) & 1) * 8 + ((tid >> 2) & 1) * 4 + ((tid >> 3) & 3), lk = (tid & 3) * 8;
;   f32x16 acc[MI][2];
; #pragma unroll
;   for (int i = 0; i < MI; ++i)
; #pragma unroll
;     for (int j = 0; j < 2; ++j)
; #pragma unroll
;       for (int r = 0; r < 16; ++r) acc[i][j][r] = 0.f;
;   u32x4 ra[MI], rb[2];
;   const int nk = K >> 5;
; #pragma unroll
;   for (int i = 0; i < MI; ++i) ra[i] = *(const u32x4*)af(m0 + lrow + 64 * i, lk);
; #pragma unroll
;   for (int i = 0; i < 2; ++i) rb[i] = *(const u32x4*)bfn(n0 + lrow + 64 * i, lk);
; #pragma unroll
;   for (int i = 0; i < MI; ++i) *(u32x4*)&As[(lrow + 64 * i) * 40 + lk] = ra[i];
; #pragma unroll
;   for (int i = 0; i < 2; ++i) *(u32x4*)&Bs[(lrow + 64 * i) * 40 + lk] = rb[i];
;   {
;     const int k1 = (nk > 1) ? 32 + lk : lk;
; #pragma unroll
;     for (int i = 0; i < MI; ++i) ra[i] = *(const u32x4*)af(m0 + lrow + 64 * i, k1);
; #pragma unroll
;     for (int i = 0; i < 2; ++i) rb[i] = *(const u32x4*)bfn(n0 + lrow + 64 * i, k1);
;   }
;   __syncthreads();
; DI void phase_inproj(const Params& p, int l, int bid, int nblk, char* smem) {
;     ...
;     if (nt >= 18 && nt < 22) gemm_tile<false, 4>(af, bfn, efN, mt * 256, nt * 128, 1024, smem);
.LBB0_747:
	s_and_b64 vcc, exec, s[0:1]
	s_cbranch_vccz .LBB0_416
	v_lshrrev_b32_e32 v128, 6, v218
	v_bfe_u32 v129, v218, 5, 1
	v_bfe_u32 v130, v218, 2, 1
	v_bfe_u32 v131, v218, 3, 2
	v_lshlrev_b32_e32 v132, 4, v128
	v_lshl_add_u32 v132, v129, 3, v132
	v_lshl_add_u32 v132, v130, 2, v132
	v_add_u32_e32 v132, v132, v131
	v_and_b32_e32 v133, 3, v218
	v_lshlrev_b32_e32 v133, 4, v133
	v_lshl_add_u32 v200, v132, 11, v133
	v_mul_u32_u24_e32 v134, 80, v132
	v_add_u32_e32 v202, v134, v133
	v_and_b32_e32 v135, 31, v218
	v_lshrrev_b32_e32 v136, 7, v218
	v_bfe_u32 v137, v218, 6, 1
	v_lshl_add_u32 v136, v136, 7, v135
	v_lshl_add_u32 v137, v137, 6, v135
	v_mul_u32_u24_e32 v136, 80, v136
	v_mul_u32_u24_e32 v137, 80, v137
	v_lshl_add_u32 v206, v129, 4, v136
	v_lshl_add_u32 v207, v129, 4, v137
	s_add_i32 s56, s73, 0
	s_lshl_b32 s56, s56, 11
	s_add_u32 s26, s6, s56
	s_addc_u32 s27, s7, 0
	s_add_i32 s56, s73, 64
	s_lshl_b32 s56, s56, 11
	s_add_u32 s28, s6, s56
	s_addc_u32 s29, s7, 0
	s_add_i32 s56, s73, 128
	s_lshl_b32 s56, s56, 11
	s_add_u32 s30, s6, s56
	s_addc_u32 s31, s7, 0
	s_add_i32 s56, s73, 192
	s_lshl_b32 s56, s56, 11
	s_add_u32 s36, s6, s56
	s_addc_u32 s37, s7, 0
	s_add_i32 s56, s72, 0
	s_lshl_b32 s56, s56, 11
	s_add_u32 s42, s50, s56
	s_addc_u32 s43, s51, 0
	s_add_i32 s56, s72, 64
	s_lshl_b32 s56, s56, 11
	s_add_u32 s48, s50, s56
	s_addc_u32 s49, s51, 0
	v_mov_b64_e32 v[0:1], 0
	v_mov_b64_e32 v[2:3], 0
	v_mov_b64_e32 v[4:5], 0
	v_mov_b64_e32 v[6:7], 0
	v_mov_b64_e32 v[8:9], 0
	v_mov_b64_e32 v[10:11], 0
	v_mov_b64_e32 v[12:13], 0
	v_mov_b64_e32 v[14:15], 0
	v_mov_b64_e32 v[16:17], 0
	v_mov_b64_e32 v[18:19], 0
	v_mov_b64_e32 v[20:21], 0
	v_mov_b64_e32 v[22:23], 0
	v_mov_b64_e32 v[24:25], 0
	v_mov_b64_e32 v[26:27], 0
	v_mov_b64_e32 v[28:29], 0
	v_mov_b64_e32 v[30:31], 0
	v_mov_b64_e32 v[32:33], 0
	v_mov_b64_e32 v[34:35], 0
	v_mov_b64_e32 v[36:37], 0
	v_mov_b64_e32 v[38:39], 0
	v_mov_b64_e32 v[40:41], 0
	v_mov_b64_e32 v[42:43], 0
	v_mov_b64_e32 v[44:45], 0
	v_mov_b64_e32 v[46:47], 0
	v_mov_b64_e32 v[48:49], 0
	v_mov_b64_e32 v[50:51], 0
	v_mov_b64_e32 v[52:53], 0
	v_mov_b64_e32 v[54:55], 0
	v_mov_b64_e32 v[56:57], 0
	v_mov_b64_e32 v[58:59], 0
	v_mov_b64_e32 v[60:61], 0
	v_mov_b64_e32 v[62:63], 0
	v_mov_b64_e32 v[64:65], 0
	v_mov_b64_e32 v[66:67], 0
	v_mov_b64_e32 v[68:69], 0
	v_mov_b64_e32 v[70:71], 0
	v_mov_b64_e32 v[72:73], 0
	v_mov_b64_e32 v[74:75], 0
	v_mov_b64_e32 v[76:77], 0
	v_mov_b64_e32 v[78:79], 0
	v_mov_b64_e32 v[80:81], 0
	v_mov_b64_e32 v[82:83], 0
	v_mov_b64_e32 v[84:85], 0
	v_mov_b64_e32 v[86:87], 0
	v_mov_b64_e32 v[88:89], 0
	v_mov_b64_e32 v[90:91], 0
	v_mov_b64_e32 v[92:93], 0
	v_mov_b64_e32 v[94:95], 0
	v_mov_b64_e32 v[96:97], 0
	v_mov_b64_e32 v[98:99], 0
	v_mov_b64_e32 v[100:101], 0
	v_mov_b64_e32 v[102:103], 0
	v_mov_b64_e32 v[104:105], 0
	v_mov_b64_e32 v[106:107], 0
	v_mov_b64_e32 v[108:109], 0
	v_mov_b64_e32 v[110:111], 0
	v_mov_b64_e32 v[112:113], 0
	v_mov_b64_e32 v[114:115], 0
	v_mov_b64_e32 v[116:117], 0
	v_mov_b64_e32 v[118:119], 0
	v_mov_b64_e32 v[120:121], 0
	v_mov_b64_e32 v[122:123], 0
	v_mov_b64_e32 v[124:125], 0
	v_mov_b64_e32 v[126:127], 0
	s_mov_b32 s64, 0
	v_add_u32_e32 v201, s64, v200
	global_load_dwordx4 v[128:131], v201, s[26:27]
	global_load_dwordx4 v[152:155], v201, s[26:27] offset:64
	global_load_dwordx4 v[132:135], v201, s[28:29]
	global_load_dwordx4 v[156:159], v201, s[28:29] offset:64
	global_load_dwordx4 v[136:139], v201, s[30:31]
	global_load_dwordx4 v[160:163], v201, s[30:31] offset:64
	global_load_dwordx4 v[140:143], v201, s[36:37]
	global_load_dwordx4 v[164:167], v201, s[36:37] offset:64
	global_load_dwordx4 v[144:147], v201, s[42:43]
	global_load_dwordx4 v[168:171], v201, s[42:43] offset:64
	global_load_dwordx4 v[148:151], v201, s[48:49]
	global_load_dwordx4 v[176:179], v201, s[48:49] offset:64
	s_add_i32 s64, s64, 0x80
	s_movk_i32 s65, 16
	s_waitcnt vmcnt(0)
	ds_write_b128 v202, v[128:131] offset:0
	ds_write_b128 v202, v[132:135] offset:5120
	ds_write_b128 v202, v[136:139] offset:10240
	ds_write_b128 v202, v[140:143] offset:15360
	ds_write_b128 v202, v[144:147] offset:40960
	ds_write_b128 v202, v[148:151] offset:46080
	s_waitcnt lgkmcnt(0)
	s_barrier
	ds_read_b128 v[196:199], v207 offset:40960
	ds_read_b128 v[228:231], v207 offset:43520
	ds_read_b128 v[180:183], v206 offset:0
	ds_read_b128 v[184:187], v206 offset:2560
	ds_read_b128 v[188:191], v206 offset:5120
	ds_read_b128 v[192:195], v206 offset:7680
; template <bool SWAP, int MI, class AF, class BF, class EF>
; DI void gemm_tile(const AF& af, const BF& bfn, const EF& ef, int m0, int n0, int K, char* smem) {
;     ...
;   for (int kt = 0; kt < nk; ++kt) {
;     const int cur = kt & 1;
;     const u16* Ab = As + cur * AROWS * 40;
;     const u16* Bb = Bs + cur * 128 * 40;
; #pragma unroll
;     for (int ks = 0; ks < 2; ++ks) {
;       bf16x8 a[MI], b[2];
; #pragma unroll
;       for (int i = 0; i < MI; ++i) a[i] = *(const bf16x8*)&Ab[(wm * (MI * 32) + i * 32 + l32) * 40 + ks * 16 + h * 8];
; #pragma unroll
;       for (int i = 0; i < 2; ++i) b[i] = *(const bf16x8*)&Bb[(wn * 64 + i * 32 + l32) * 40 + ks * 16 + h * 8];
; #pragma unroll
;       for (int i = 0; i < MI; ++i)
; #pragma unroll
;         for (int j = 0; j < 2; ++j)
;           acc[i][j] = SWAP ? __builtin_amdgcn_mfma_f32_32x32x16_bf16(b[j], a[i], acc[i][j], 0, 0, 0)
;                            : __builtin_amdgcn_mfma_f32_32x32x16_bf16(a[i], b[j], acc[i][j], 0, 0, 0);
;     }
;     {
;       u16* An = As + (cur ^ 1) * AROWS * 40;
;       u16* Bn = Bs + (cur ^ 1) * 128 * 40;
; #pragma unroll
;       for (int i = 0; i < MI; ++i) *(u32x4*)&An[(lrow + 64 * i) * 40 + lk] = ra[i];
; #pragma unroll
;       for (int i = 0; i < 2; ++i) *(u32x4*)&Bn[(lrow + 64 * i) * 40 + lk] = rb[i];
;       const int kn = (kt + 2 < nk) ? kt + 2 : nk - 1;
;       const int k0 = kn * 32 + lk;
; #pragma unroll
;       for (int i = 0; i < MI; ++i) ra[i] = *(const u32x4*)af(m0 + lrow + 64 * i, k0);
; #pragma unroll
;       for (int i = 0; i < 2; ++i) rb[i] = *(const u32x4*)bfn(n0 + lrow + 64 * i, k0);
;     }
;     __syncthreads();
;   }
.Lgemm_ipn_loop:
	ds_read_b128 v[232:235], v207 offset:40992
	ds_read_b128 v[236:239], v207 offset:43552
	ds_read_b128 v[220:223], v206 offset:32
	ds_read_b128 v[240:243], v206 offset:2592
	ds_read_b128 v[244:247], v206 offset:5152
	ds_read_b128 v[248:251], v206 offset:7712
	s_waitcnt lgkmcnt(9)
	v_mfma_f32_32x32x16_bf16 v[112:127], v[180:183], v[196:199], v[112:127]
	v_mfma_f32_32x32x16_bf16 v[96:111], v[180:183], v[228:231], v[96:111]
	s_waitcnt lgkmcnt(8)
	v_mfma_f32_32x32x16_bf16 v[80:95], v[184:187], v[196:199], v[80:95]
	v_mfma_f32_32x32x16_bf16 v[64:79], v[184:187], v[228:231], v[64:79]
	ds_write_b128 v202, v[152:155] offset:20480
	ds_write_b128 v202, v[156:159] offset:25600
	ds_write_b128 v202, v[160:163] offset:30720
	ds_write_b128 v202, v[164:167] offset:35840
	ds_write_b128 v202, v[168:171] offset:51200
	ds_write_b128 v202, v[176:179] offset:56320
	v_add_u32_e32 v201, s64, v200
	global_load_dwordx4 v[128:131], v201, s[26:27]
	global_load_dwordx4 v[152:155], v201, s[26:27] offset:64
	global_load_dwordx4 v[132:135], v201, s[28:29]
	global_load_dwordx4 v[156:159], v201, s[28:29] offset:64
	global_load_dwordx4 v[136:139], v201, s[30:31]
	global_load_dwordx4 v[160:163], v201, s[30:31] offset:64
	global_load_dwordx4 v[140:143], v201, s[36:37]
	global_load_dwordx4 v[164:167], v201, s[36:37] offset:64
	global_load_dwordx4 v[144:147], v201, s[42:43]
	global_load_dwordx4 v[168:171], v201, s[42:43] offset:64
	global_load_dwordx4 v[148:151], v201, s[48:49]
	global_load_dwordx4 v[176:179], v201, s[48:49] offset:64
	s_add_i32 s64, s64, 0x80
	s_min_u32 s64, s64, 0x780
	s_waitcnt lgkmcnt(13)
	v_mfma_f32_32x32x16_bf16 v[48:63], v[188:191], v[196:199], v[48:63]
	v_mfma_f32_32x32x16_bf16 v[32:47], v[188:191], v[228:231], v[32:47]
	s_waitcnt lgkmcnt(12)
	v_mfma_f32_32x32x16_bf16 v[16:31], v[192:195], v[196:199], v[16:31]
	v_mfma_f32_32x32x16_bf16 v[0:15], v[192:195], v[228:231], v[0:15]
	s_waitcnt lgkmcnt(0)
	s_barrier
	ds_read_b128 v[196:199], v207 offset:51200
	ds_read_b128 v[228:231], v207 offset:53760
	ds_read_b128 v[180:183], v206 offset:20480
	ds_read_b128 v[184:187], v206 offset:23040
	ds_read_b128 v[188:191], v206 offset:25600
	ds_read_b128 v[192:195], v206 offset:28160
	v_mfma_f32_32x32x16_bf16 v[112:127], v[220:223], v[232:235], v[112:127]
	v_mfma_f32_32x32x16_bf16 v[96:111], v[220:223], v[236:239], v[96:111]
	v_mfma_f32_32x32x16_bf16 v[80:95], v[240:243], v[232:235], v[80:95]
	v_mfma_f32_32x32x16_bf16 v[64:79], v[240:243], v[236:239], v[64:79]
	v_mfma_f32_32x32x16_bf16 v[48:63], v[244:247], v[232:235], v[48:63]
	v_mfma_f32_32x32x16_bf16 v[32:47], v[244:247], v[236:239], v[32:47]
	v_mfma_f32_32x32x16_bf16 v[16:31], v[248:251], v[232:235], v[16:31]
	v_mfma_f32_32x32x16_bf16 v[0:15], v[248:251], v[236:239], v[0:15]
	ds_read_b128 v[232:235], v207 offset:51232
	ds_read_b128 v[236:239], v207 offset:53792
	ds_read_b128 v[220:223], v206 offset:20512
	ds_read_b128 v[240:243], v206 offset:23072
	ds_read_b128 v[244:247], v206 offset:25632
	ds_read_b128 v[248:251], v206 offset:28192
	s_waitcnt lgkmcnt(9)
	v_mfma_f32_32x32x16_bf16 v[112:127], v[180:183], v[196:199], v[112:127]
	v_mfma_f32_32x32x16_bf16 v[96:111], v[180:183], v[228:231], v[96:111]
	s_waitcnt lgkmcnt(8)
	v_mfma_f32_32x32x16_bf16 v[80:95], v[184:187], v[196:199], v[80:95]
	v_mfma_f32_32x32x16_bf16 v[64:79], v[184:187], v[228:231], v[64:79]
	s_waitcnt vmcnt(0)
	ds_write_b128 v202, v[128:131] offset:0
	ds_write_b128 v202, v[132:135] offset:5120
	ds_write_b128 v202, v[136:139] offset:10240
	ds_write_b128 v202, v[140:143] offset:15360
	ds_write_b128 v202, v[144:147] offset:40960
	ds_write_b128 v202, v[148:151] offset:46080
	s_waitcnt lgkmcnt(13)
	v_mfma_f32_32x32x16_bf16 v[48:63], v[188:191], v[196:199], v[48:63]
	v_mfma_f32_32x32x16_bf16 v[32:47], v[188:191], v[228:231], v[32:47]
	s_waitcnt lgkmcnt(12)
	v_mfma_f32_32x32x16_bf16 v[16:31], v[192:195], v[196:199], v[16:31]
	v_mfma_f32_32x32x16_bf16 v[0:15], v[192:195], v[228:231], v[0:15]
	s_waitcnt lgkmcnt(0)
	s_barrier
	ds_read_b128 v[196:199], v207 offset:40960
	ds_read_b128 v[228:231], v207 offset:43520
	ds_read_b128 v[180:183], v206 offset:0
	ds_read_b128 v[184:187], v206 offset:2560
	ds_read_b128 v[188:191], v206 offset:5120
	ds_read_b128 v[192:195], v206 offset:7680
	v_mfma_f32_32x32x16_bf16 v[112:127], v[220:223], v[232:235], v[112:127]
	v_mfma_f32_32x32x16_bf16 v[96:111], v[220:223], v[236:239], v[96:111]
	v_mfma_f32_32x32x16_bf16 v[80:95], v[240:243], v[232:235], v[80:95]
	v_mfma_f32_32x32x16_bf16 v[64:79], v[240:243], v[236:239], v[64:79]
	v_mfma_f32_32x32x16_bf16 v[48:63], v[244:247], v[232:235], v[48:63]
	v_mfma_f32_32x32x16_bf16 v[32:47], v[244:247], v[236:239], v[32:47]
	v_mfma_f32_32x32x16_bf16 v[16:31], v[248:251], v[232:235], v[16:31]
	v_mfma_f32_32x32x16_bf16 v[0:15], v[248:251], v[236:239], v[0:15]
	s_add_i32 s65, s65, -1
	s_cmp_lg_u32 s65, 0
	s_cbranch_scc1 .Lgemm_ipn_loop
; DI u32 pack2(float a, float b) { return (u32)f2bf(a) | ((u32)f2bf(b) << 16); }
; template <bool SWAP, int MI, class AF, class BF, class EF>
; DI void gemm_tile(const AF& af, const BF& bfn, const EF& ef, int m0, int n0, int K, char* smem) {
;     ...
; #pragma unroll
;   for (int i = 0; i < MI; ++i)
; #pragma unroll
;     for (int j = 0; j < 2; ++j)
; #pragma unroll
;       for (int rg = 0; rg < 4; ++rg) {
;         const int m = SWAP ? (m0 + wm * (MI * 32) + i * 32 + l32) : (m0 + wm * (MI * 32) + i * 32 + rg * 8 + h * 4);
;         const int n = SWAP ? (n0 + wn * 64 + j * 32 + rg * 8 + h * 4) : (n0 + wn * 64 + j * 32 + l32);
;         ef(m, n, acc[i][j][rg * 4 + 0], acc[i][j][rg * 4 + 1], acc[i][j][rg * 4 + 2], acc[i][j][rg * 4 + 3]);
;       }
; DI void phase_inproj(const Params& p, int l, int bid, int nblk, char* smem) {
;     ...
;   auto efN = [=](int m, int n, float v0, float v1, float v2, float v3) {
;     const int b = m / TPB, pos = m % TPB, np = n - 2304;
;     uint2 o = {pack2(v0, v1), pack2(v2, v3)};
;     *(uint2*)&PQT[((size_t)(b * 512 + np)) * TPB + pos] = o;
;   };
	s_waitcnt lgkmcnt(0)
	s_waitcnt vmcnt(0)
	v_and_b32_e32 v128, 31, v218
	v_lshrrev_b32_e32 v129, 7, v218
	v_bfe_u32 v130, v218, 5, 1
	v_bfe_u32 v131, v218, 6, 1
	v_lshl_add_u32 v128, v131, 6, v128
	v_mul_u32_u24_e32 v128, 528, v128
	v_lshlrev_b32_e32 v129, 8, v129
	v_lshl_add_u32 v129, v130, 3, v129
	v_add_u32_e32 v128, v128, v129
	s_nop 7
	v_cvt_pk_bf16_f32 v112, v112, v113
	v_cvt_pk_bf16_f32 v113, v114, v115
	v_cvt_pk_bf16_f32 v116, v116, v117
	v_cvt_pk_bf16_f32 v117, v118, v119
	v_cvt_pk_bf16_f32 v120, v120, v121
	v_cvt_pk_bf16_f32 v121, v122, v123
	v_cvt_pk_bf16_f32 v124, v124, v125
	v_cvt_pk_bf16_f32 v125, v126, v127
	ds_write_b64 v128, v[112:113] offset:0
	ds_write_b64 v128, v[116:117] offset:16
	ds_write_b64 v128, v[120:121] offset:32
	ds_write_b64 v128, v[124:125] offset:48
	v_cvt_pk_bf16_f32 v96, v96, v97
	v_cvt_pk_bf16_f32 v97, v98, v99
	v_cvt_pk_bf16_f32 v100, v100, v101
	v_cvt_pk_bf16_f32 v101, v102, v103
	v_cvt_pk_bf16_f32 v104, v104, v105
	v_cvt_pk_bf16_f32 v105, v106, v107
	v_cvt_pk_bf16_f32 v108, v108, v109
	v_cvt_pk_bf16_f32 v109, v110, v111
	ds_write_b64 v128, v[96:97] offset:16896
	ds_write_b64 v128, v[100:101] offset:16912
	ds_write_b64 v128, v[104:105] offset:16928
	ds_write_b64 v128, v[108:109] offset:16944
	v_cvt_pk_bf16_f32 v80, v80, v81
	v_cvt_pk_bf16_f32 v81, v82, v83
	v_cvt_pk_bf16_f32 v84, v84, v85
	v_cvt_pk_bf16_f32 v85, v86, v87
	v_cvt_pk_bf16_f32 v88, v88, v89
	v_cvt_pk_bf16_f32 v89, v90, v91
	v_cvt_pk_bf16_f32 v92, v92, v93
	v_cvt_pk_bf16_f32 v93, v94, v95
	ds_write_b64 v128, v[80:81] offset:64
	ds_write_b64 v128, v[84:85] offset:80
	ds_write_b64 v128, v[88:89] offset:96
	ds_write_b64 v128, v[92:93] offset:112
	v_cvt_pk_bf16_f32 v64, v64, v65
	v_cvt_pk_bf16_f32 v65, v66, v67
	v_cvt_pk_bf16_f32 v68, v68, v69
	v_cvt_pk_bf16_f32 v69, v70, v71
	v_cvt_pk_bf16_f32 v72, v72, v73
	v_cvt_pk_bf16_f32 v73, v74, v75
	v_cvt_pk_bf16_f32 v76, v76, v77
	v_cvt_pk_bf16_f32 v77, v78, v79
	ds_write_b64 v128, v[64:65] offset:16960
	ds_write_b64 v128, v[68:69] offset:16976
	ds_write_b64 v128, v[72:73] offset:16992
	ds_write_b64 v128, v[76:77] offset:17008
	v_cvt_pk_bf16_f32 v48, v48, v49
	v_cvt_pk_bf16_f32 v49, v50, v51
	v_cvt_pk_bf16_f32 v52, v52, v53
	v_cvt_pk_bf16_f32 v53, v54, v55
	v_cvt_pk_bf16_f32 v56, v56, v57
	v_cvt_pk_bf16_f32 v57, v58, v59
	v_cvt_pk_bf16_f32 v60, v60, v61
	v_cvt_pk_bf16_f32 v61, v62, v63
	ds_write_b64 v128, v[48:49] offset:128
	ds_write_b64 v128, v[52:53] offset:144
	ds_write_b64 v128, v[56:57] offset:160
	ds_write_b64 v128, v[60:61] offset:176
	v_cvt_pk_bf16_f32 v32, v32, v33
	v_cvt_pk_bf16_f32 v33, v34, v35
	v_cvt_pk_bf16_f32 v36, v36, v37
	v_cvt_pk_bf16_f32 v37, v38, v39
	v_cvt_pk_bf16_f32 v40, v40, v41
	v_cvt_pk_bf16_f32 v41, v42, v43
	v_cvt_pk_bf16_f32 v44, v44, v45
	v_cvt_pk_bf16_f32 v45, v46, v47
	ds_write_b64 v128, v[32:33] offset:17024
	ds_write_b64 v128, v[36:37] offset:17040
	ds_write_b64 v128, v[40:41] offset:17056
	ds_write_b64 v128, v[44:45] offset:17072
	v_cvt_pk_bf16_f32 v16, v16, v17
	v_cvt_pk_bf16_f32 v17, v18, v19
	v_cvt_pk_bf16_f32 v20, v20, v21
	v_cvt_pk_bf16_f32 v21, v22, v23
	v_cvt_pk_bf16_f32 v24, v24, v25
	v_cvt_pk_bf16_f32 v25, v26, v27
	v_cvt_pk_bf16_f32 v28, v28, v29
	v_cvt_pk_bf16_f32 v29, v30, v31
	ds_write_b64 v128, v[16:17] offset:192
	ds_write_b64 v128, v[20:21] offset:208
	ds_write_b64 v128, v[24:25] offset:224
	ds_write_b64 v128, v[28:29] offset:240
	v_cvt_pk_bf16_f32 v0, v0, v1
	v_cvt_pk_bf16_f32 v1, v2, v3
	v_cvt_pk_bf16_f32 v4, v4, v5
	v_cvt_pk_bf16_f32 v5, v6, v7
	v_cvt_pk_bf16_f32 v8, v8, v9
	v_cvt_pk_bf16_f32 v9, v10, v11
	v_cvt_pk_bf16_f32 v12, v12, v13
	v_cvt_pk_bf16_f32 v13, v14, v15
	ds_write_b64 v128, v[0:1] offset:17088
	ds_write_b64 v128, v[4:5] offset:17104
	ds_write_b64 v128, v[8:9] offset:17120
	ds_write_b64 v128, v[12:13] offset:17136
	s_mul_hi_u32 s36, s73, 0x38e38e39
	s_lshr_b32 s36, s36, 9
	s_mul_i32 s37, s36, 0x900
	s_sub_u32 s37, s73, s37
	s_lshl_b32 s36, s36, 9
	s_add_i32 s36, s36, s72
	s_add_i32 s36, s36, 0xfffff700
	s_mul_i32 s36, s36, 0x900
	s_add_i32 s36, s36, s37
	s_lshl_b32 s16, s36, 1
	s_add_u32 s16, s16, 0x13200000
	s_add_u32 s16, s96, s16
	s_addc_u32 s17, s97, 0
	s_movk_i32 s38, 0x1200
	s_mov_b32 s39, 0x9000
	v_lshrrev_b32_e32 v129, 5, v218
	v_and_b32_e32 v130, 31, v218
	v_mul_u32_u24_e32 v131, 528, v129
	v_mul_lo_u32 v132, v129, s38
	v_lshl_add_u32 v131, v130, 4, v131
	v_lshl_add_u32 v132, v130, 4, v132
	s_waitcnt lgkmcnt(0)
	s_barrier
	ds_read_b128 v[0:3], v131 offset:0
	ds_read_b128 v[4:7], v131 offset:4224
	ds_read_b128 v[8:11], v131 offset:8448
	ds_read_b128 v[12:15], v131 offset:12672
	ds_read_b128 v[16:19], v131 offset:16896
	ds_read_b128 v[20:23], v131 offset:21120
	ds_read_b128 v[24:27], v131 offset:25344
	ds_read_b128 v[28:31], v131 offset:29568
	ds_read_b128 v[32:35], v131 offset:33792
	ds_read_b128 v[36:39], v131 offset:38016
	ds_read_b128 v[40:43], v131 offset:42240
	ds_read_b128 v[44:47], v131 offset:46464
	ds_read_b128 v[48:51], v131 offset:50688
	ds_read_b128 v[52:55], v131 offset:54912
	ds_read_b128 v[56:59], v131 offset:59136
	ds_read_b128 v[60:63], v131 offset:63360
	s_waitcnt lgkmcnt(15)
	global_store_dwordx4 v132, v[0:3], s[16:17]
	s_add_u32 s16, s16, s39
	s_addc_u32 s17, s17, 0
	s_waitcnt lgkmcnt(14)
	global_store_dwordx4 v132, v[4:7], s[16:17]
	s_add_u32 s16, s16, s39
	s_addc_u32 s17, s17, 0
	s_waitcnt lgkmcnt(13)
	global_store_dwordx4 v132, v[8:11], s[16:17]
	s_add_u32 s16, s16, s39
	s_addc_u32 s17, s17, 0
	s_waitcnt lgkmcnt(12)
	global_store_dwordx4 v132, v[12:15], s[16:17]
	s_add_u32 s16, s16, s39
	s_addc_u32 s17, s17, 0
	s_waitcnt lgkmcnt(11)
	global_store_dwordx4 v132, v[16:19], s[16:17]
	s_add_u32 s16, s16, s39
	s_addc_u32 s17, s17, 0
	s_waitcnt lgkmcnt(10)
	global_store_dwordx4 v132, v[20:23], s[16:17]
	s_add_u32 s16, s16, s39
	s_addc_u32 s17, s17, 0
	s_waitcnt lgkmcnt(9)
	global_store_dwordx4 v132, v[24:27], s[16:17]
	s_add_u32 s16, s16, s39
	s_addc_u32 s17, s17, 0
	s_waitcnt lgkmcnt(8)
	global_store_dwordx4 v132, v[28:31], s[16:17]
	s_add_u32 s16, s16, s39
	s_addc_u32 s17, s17, 0
	s_waitcnt lgkmcnt(7)
	global_store_dwordx4 v132, v[32:35], s[16:17]
	s_add_u32 s16, s16, s39
	s_addc_u32 s17, s17, 0
	s_waitcnt lgkmcnt(6)
	global_store_dwordx4 v132, v[36:39], s[16:17]
	s_add_u32 s16, s16, s39
	s_addc_u32 s17, s17, 0
	s_waitcnt lgkmcnt(5)
	global_store_dwordx4 v132, v[40:43], s[16:17]
	s_add_u32 s16, s16, s39
	s_addc_u32 s17, s17, 0
	s_waitcnt lgkmcnt(4)
	global_store_dwordx4 v132, v[44:47], s[16:17]
	s_add_u32 s16, s16, s39
	s_addc_u32 s17, s17, 0
	s_waitcnt lgkmcnt(3)
	global_store_dwordx4 v132, v[48:51], s[16:17]
	s_add_u32 s16, s16, s39
	s_addc_u32 s17, s17, 0
	s_waitcnt lgkmcnt(2)
	global_store_dwordx4 v132, v[52:55], s[16:17]
	s_add_u32 s16, s16, s39
	s_addc_u32 s17, s17, 0
	s_waitcnt lgkmcnt(1)
	global_store_dwordx4 v132, v[56:59], s[16:17]
	s_add_u32 s16, s16, s39
	s_addc_u32 s17, s17, 0
	s_waitcnt lgkmcnt(0)
	global_store_dwordx4 v132, v[60:63], s[16:17]
	s_barrier
	s_branch .LBB0_416
